# cross-lane row-max exchange moved into the rare running-max update path of the selected loop
# speedup vs baseline: 1.0041x; 1.0041x over previous
; __device__ __forceinline__ float xq_max(float v) { const auto r = __builtin_amdgcn_permlane16_swap(__float_as_uint(v), __float_as_uint(v), false, false); return xhalf_max(fmaxf(__uint_as_float(r[0]), __uint_as_float(r[1]))); }
; __device__ __forceinline__ void flash16_compute(bool domask, const bf16x8 (&kf)[4], const bf16x8 (&vf)[4], const bf16x8 (&q)[2], int x0, unsigned span, float& m, float& l, f32x4v (&O)[4]) {
;     ...
;     float sc[8] = {s0[0], s0[1], s0[2], s0[3], s1[0], s1[1], s1[2], s1[3]};
;     if (domask) {
; #pragma unroll
;         for (int j = 0; j < 8; ++j) sc[j] = ((unsigned)(x0 + j) <= span) ? sc[j] : -1e30f;
;     }
;     float mx = fmaxf(fmaxf(fmaxf(sc[0], sc[1]), fmaxf(sc[2], sc[3])), fmaxf(fmaxf(sc[4], sc[5]), fmaxf(sc[6], sc[7])));
;     mx = xq_max(mx);
;     const bool upd = mx > m + SM_THR;
;     if (__ballot(upd) != 0ull) {
.Lsel_qk2_Aa:
	v_mfma_f32_16x16x32_bf16 v[2:5], v[118:121], v[98:101], v[2:5]
	v_mfma_f32_16x16x32_bf16 v[6:9], v[126:129], v[98:101], v[6:9]
	s_nop 6
	v_max3_f32 v14, v2, v3, v4
	v_max3_f32 v16, v5, v6, v7
	v_max_f32_e32 v17, v8, v9
	v_max3_f32 v14, v14, v16, v17
	v_cmp_gt_f32_e32 vcc, v14, v94
	s_cbranch_vccnz .Lsel_upd_Aa

; __device__ __forceinline__ float xq_max(float v) { const auto r = __builtin_amdgcn_permlane16_swap(__float_as_uint(v), __float_as_uint(v), false, false); return xhalf_max(fmaxf(__uint_as_float(r[0]), __uint_as_float(r[1]))); }
; __device__ __forceinline__ void flash16_compute(bool domask, const bf16x8 (&kf)[4], const bf16x8 (&vf)[4], const bf16x8 (&q)[2], int x0, unsigned span, float& m, float& l, f32x4v (&O)[4]) {
;     ...
;     float sc[8] = {s0[0], s0[1], s0[2], s0[3], s1[0], s1[1], s1[2], s1[3]};
;     if (domask) {
; #pragma unroll
;         for (int j = 0; j < 8; ++j) sc[j] = ((unsigned)(x0 + j) <= span) ? sc[j] : -1e30f;
;     }
;     float mx = fmaxf(fmaxf(fmaxf(sc[0], sc[1]), fmaxf(sc[2], sc[3])), fmaxf(fmaxf(sc[4], sc[5]), fmaxf(sc[6], sc[7])));
;     mx = xq_max(mx);
;     const bool upd = mx > m + SM_THR;
;     if (__ballot(upd) != 0ull) {
.Lsel_qk2_Ab:
	v_mfma_f32_16x16x32_bf16 v[2:5], v[118:121], v[106:109], v[2:5]
	v_mfma_f32_16x16x32_bf16 v[6:9], v[126:129], v[106:109], v[6:9]
	s_nop 6
	v_max3_f32 v14, v2, v3, v4
	v_max3_f32 v16, v5, v6, v7
	v_max_f32_e32 v17, v8, v9
	v_max3_f32 v14, v14, v16, v17
	v_cmp_gt_f32_e32 vcc, v14, v95
	s_cbranch_vccnz .Lsel_upd_Ab

; __device__ __forceinline__ float xq_max(float v) { const auto r = __builtin_amdgcn_permlane16_swap(__float_as_uint(v), __float_as_uint(v), false, false); return xhalf_max(fmaxf(__uint_as_float(r[0]), __uint_as_float(r[1]))); }
; __device__ __forceinline__ void flash16_compute(bool domask, const bf16x8 (&kf)[4], const bf16x8 (&vf)[4], const bf16x8 (&q)[2], int x0, unsigned span, float& m, float& l, f32x4v (&O)[4]) {
;     ...
;     float sc[8] = {s0[0], s0[1], s0[2], s0[3], s1[0], s1[1], s1[2], s1[3]};
;     if (domask) {
; #pragma unroll
;         for (int j = 0; j < 8; ++j) sc[j] = ((unsigned)(x0 + j) <= span) ? sc[j] : -1e30f;
;     }
;     float mx = fmaxf(fmaxf(fmaxf(sc[0], sc[1]), fmaxf(sc[2], sc[3])), fmaxf(fmaxf(sc[4], sc[5]), fmaxf(sc[6], sc[7])));
;     mx = xq_max(mx);
;     const bool upd = mx > m + SM_THR;
;     if (__ballot(upd) != 0ull) {
.Lsel_qk2_Ba:
	v_mfma_f32_16x16x32_bf16 v[2:5], v[150:153], v[98:101], v[2:5]
	v_mfma_f32_16x16x32_bf16 v[6:9], v[158:161], v[98:101], v[6:9]
	s_nop 6
	v_max3_f32 v14, v2, v3, v4
	v_max3_f32 v16, v5, v6, v7
	v_max_f32_e32 v17, v8, v9
	v_max3_f32 v14, v14, v16, v17
	v_cmp_gt_f32_e32 vcc, v14, v94
	s_cbranch_vccnz .Lsel_upd_Ba

; __device__ __forceinline__ float xq_max(float v) { const auto r = __builtin_amdgcn_permlane16_swap(__float_as_uint(v), __float_as_uint(v), false, false); return xhalf_max(fmaxf(__uint_as_float(r[0]), __uint_as_float(r[1]))); }
; __device__ __forceinline__ void flash16_compute(bool domask, const bf16x8 (&kf)[4], const bf16x8 (&vf)[4], const bf16x8 (&q)[2], int x0, unsigned span, float& m, float& l, f32x4v (&O)[4]) {
;     ...
;     float sc[8] = {s0[0], s0[1], s0[2], s0[3], s1[0], s1[1], s1[2], s1[3]};
;     if (domask) {
; #pragma unroll
;         for (int j = 0; j < 8; ++j) sc[j] = ((unsigned)(x0 + j) <= span) ? sc[j] : -1e30f;
;     }
;     float mx = fmaxf(fmaxf(fmaxf(sc[0], sc[1]), fmaxf(sc[2], sc[3])), fmaxf(fmaxf(sc[4], sc[5]), fmaxf(sc[6], sc[7])));
;     mx = xq_max(mx);
;     const bool upd = mx > m + SM_THR;
;     if (__ballot(upd) != 0ull) {
.Lsel_qk2_Bb:
	v_mfma_f32_16x16x32_bf16 v[2:5], v[150:153], v[106:109], v[2:5]
	v_mfma_f32_16x16x32_bf16 v[6:9], v[158:161], v[106:109], v[6:9]
	s_nop 6
	v_max3_f32 v14, v2, v3, v4
	v_max3_f32 v16, v5, v6, v7
	v_max_f32_e32 v17, v8, v9
	v_max3_f32 v14, v14, v16, v17
	v_cmp_gt_f32_e32 vcc, v14, v95
	s_cbranch_vccnz .Lsel_upd_Bb

; __device__ __forceinline__ float xq_max(float v) { const auto r = __builtin_amdgcn_permlane16_swap(__float_as_uint(v), __float_as_uint(v), false, false); return xhalf_max(fmaxf(__uint_as_float(r[0]), __uint_as_float(r[1]))); }
; __device__ __forceinline__ void flash16_compute(bool domask, const bf16x8 (&kf)[4], const bf16x8 (&vf)[4], const bf16x8 (&q)[2], int x0, unsigned span, float& m, float& l, f32x4v (&O)[4]) {
;     ...
;     float sc[8] = {s0[0], s0[1], s0[2], s0[3], s1[0], s1[1], s1[2], s1[3]};
;     if (domask) {
; #pragma unroll
;         for (int j = 0; j < 8; ++j) sc[j] = ((unsigned)(x0 + j) <= span) ? sc[j] : -1e30f;
;     }
;     float mx = fmaxf(fmaxf(fmaxf(sc[0], sc[1]), fmaxf(sc[2], sc[3])), fmaxf(fmaxf(sc[4], sc[5]), fmaxf(sc[6], sc[7])));
;     mx = xq_max(mx);
;     const bool upd = mx > m + SM_THR;
;     if (__ballot(upd) != 0ull) {
.Lsel_qk2_Ca:
	v_mfma_f32_16x16x32_bf16 v[2:5], v[182:185], v[98:101], v[2:5]
	v_mfma_f32_16x16x32_bf16 v[6:9], v[190:193], v[98:101], v[6:9]
	s_nop 6
	v_max3_f32 v14, v2, v3, v4
	v_max3_f32 v16, v5, v6, v7
	v_max_f32_e32 v17, v8, v9
	v_max3_f32 v14, v14, v16, v17
	v_cmp_gt_f32_e32 vcc, v14, v94
	s_cbranch_vccnz .Lsel_upd_Ca

; __device__ __forceinline__ float xq_max(float v) { const auto r = __builtin_amdgcn_permlane16_swap(__float_as_uint(v), __float_as_uint(v), false, false); return xhalf_max(fmaxf(__uint_as_float(r[0]), __uint_as_float(r[1]))); }
; __device__ __forceinline__ void flash16_compute(bool domask, const bf16x8 (&kf)[4], const bf16x8 (&vf)[4], const bf16x8 (&q)[2], int x0, unsigned span, float& m, float& l, f32x4v (&O)[4]) {
;     ...
;     float sc[8] = {s0[0], s0[1], s0[2], s0[3], s1[0], s1[1], s1[2], s1[3]};
;     if (domask) {
; #pragma unroll
;         for (int j = 0; j < 8; ++j) sc[j] = ((unsigned)(x0 + j) <= span) ? sc[j] : -1e30f;
;     }
;     float mx = fmaxf(fmaxf(fmaxf(sc[0], sc[1]), fmaxf(sc[2], sc[3])), fmaxf(fmaxf(sc[4], sc[5]), fmaxf(sc[6], sc[7])));
;     mx = xq_max(mx);
;     const bool upd = mx > m + SM_THR;
;     if (__ballot(upd) != 0ull) {
.Lsel_qk2_Cb:
	v_mfma_f32_16x16x32_bf16 v[2:5], v[182:185], v[106:109], v[2:5]
	v_mfma_f32_16x16x32_bf16 v[6:9], v[190:193], v[106:109], v[6:9]
	s_nop 6
	v_max3_f32 v14, v2, v3, v4
	v_max3_f32 v16, v5, v6, v7
	v_max_f32_e32 v17, v8, v9
	v_max3_f32 v14, v14, v16, v17
	v_cmp_gt_f32_e32 vcc, v14, v95
	s_cbranch_vccnz .Lsel_upd_Cb

; __device__ __forceinline__ float xq_max(float v) { const auto r = __builtin_amdgcn_permlane16_swap(__float_as_uint(v), __float_as_uint(v), false, false); return xhalf_max(fmaxf(__uint_as_float(r[0]), __uint_as_float(r[1]))); }
; __device__ __forceinline__ void flash16_compute(bool domask, const bf16x8 (&kf)[4], const bf16x8 (&vf)[4], const bf16x8 (&q)[2], int x0, unsigned span, float& m, float& l, f32x4v (&O)[4]) {
;     ...
;     float sc[8] = {s0[0], s0[1], s0[2], s0[3], s1[0], s1[1], s1[2], s1[3]};
;     if (domask) {
; #pragma unroll
;         for (int j = 0; j < 8; ++j) sc[j] = ((unsigned)(x0 + j) <= span) ? sc[j] : -1e30f;
;     }
;     float mx = fmaxf(fmaxf(fmaxf(sc[0], sc[1]), fmaxf(sc[2], sc[3])), fmaxf(fmaxf(sc[4], sc[5]), fmaxf(sc[6], sc[7])));
;     mx = xq_max(mx);
;     const bool upd = mx > m + SM_THR;
;     if (__ballot(upd) != 0ull) {
.Lsel_qk2_Da:
	v_mfma_f32_16x16x32_bf16 v[2:5], v[66:69], v[98:101], v[2:5]
	v_mfma_f32_16x16x32_bf16 v[6:9], v[74:77], v[98:101], v[6:9]
	s_nop 6
	v_max3_f32 v14, v2, v3, v4
	v_max3_f32 v16, v5, v6, v7
	v_max_f32_e32 v17, v8, v9
	v_max3_f32 v14, v14, v16, v17
	v_cmp_gt_f32_e32 vcc, v14, v94
	s_cbranch_vccnz .Lsel_upd_Da

; __device__ __forceinline__ float xq_max(float v) { const auto r = __builtin_amdgcn_permlane16_swap(__float_as_uint(v), __float_as_uint(v), false, false); return xhalf_max(fmaxf(__uint_as_float(r[0]), __uint_as_float(r[1]))); }
; __device__ __forceinline__ void flash16_compute(bool domask, const bf16x8 (&kf)[4], const bf16x8 (&vf)[4], const bf16x8 (&q)[2], int x0, unsigned span, float& m, float& l, f32x4v (&O)[4]) {
;     ...
;     float sc[8] = {s0[0], s0[1], s0[2], s0[3], s1[0], s1[1], s1[2], s1[3]};
;     if (domask) {
; #pragma unroll
;         for (int j = 0; j < 8; ++j) sc[j] = ((unsigned)(x0 + j) <= span) ? sc[j] : -1e30f;
;     }
;     float mx = fmaxf(fmaxf(fmaxf(sc[0], sc[1]), fmaxf(sc[2], sc[3])), fmaxf(fmaxf(sc[4], sc[5]), fmaxf(sc[6], sc[7])));
;     mx = xq_max(mx);
;     const bool upd = mx > m + SM_THR;
;     if (__ballot(upd) != 0ull) {
.Lsel_qk2_Db:
	v_mfma_f32_16x16x32_bf16 v[2:5], v[66:69], v[106:109], v[2:5]
	v_mfma_f32_16x16x32_bf16 v[6:9], v[74:77], v[106:109], v[6:9]
	s_nop 6
	v_max3_f32 v14, v2, v3, v4
	v_max3_f32 v16, v5, v6, v7
	v_max_f32_e32 v17, v8, v9
	v_max3_f32 v14, v14, v16, v17
	v_cmp_gt_f32_e32 vcc, v14, v95
	s_cbranch_vccnz .Lsel_upd_Db

; __device__ __forceinline__ float ex2(float x) { return __builtin_amdgcn_exp2f(x); }
; __device__ __forceinline__ float xq_max(float v) { const auto r = __builtin_amdgcn_permlane16_swap(__float_as_uint(v), __float_as_uint(v), false, false); return xhalf_max(fmaxf(__uint_as_float(r[0]), __uint_as_float(r[1]))); }
; __device__ __forceinline__ void flash16_compute(bool domask, const bf16x8 (&kf)[4], const bf16x8 (&vf)[4], const bf16x8 (&q)[2], int x0, unsigned span, float& m, float& l, f32x4v (&O)[4]) {
;     ...
;     mx = xq_max(mx);
;     const bool upd = mx > m + SM_THR;
;     if (__ballot(upd) != 0ull) {
;         const float mn = upd ? mx : m, alpha = ex2(m - mn); l *= alpha;
; #pragma unroll
;         for (int dt = 0; dt < 4; ++dt) O[dt] = O[dt] * alpha;
;         m = mn;
;     }
.Lsel_upd_Aa:
	v_mov_b32_e32 v16, v14
	s_nop 1
	v_permlane16_swap_b32_e32 v14, v16
	v_max_f32_e32 v14, v14, v16
	v_mov_b32_e32 v16, v14
	s_nop 1
	v_permlane32_swap_b32_e32 v14, v16
	v_max_f32_e32 v14, v14, v16
	v_cmp_gt_f32_e32 vcc, v14, v94
	s_nop 1
	v_cndmask_b32_e32 v16, 0, v14, vcc
	v_sub_f32_e32 v17, v14, v240
	v_cndmask_b32_e32 v17, v236, v17, vcc
	v_sub_f32_e32 v15, v236, v17
	v_exp_f32_e32 v15, v15
	v_mov_b32_e32 v236, v17
	v_cndmask_b32_e64 v240, v240, -v17, vcc
	v_cndmask_b32_e32 v94, v94, v96, vcc
	v_mul_f32_e32 v238, v238, v15
	v_mul_f32_e32 v34, v34, v15
	v_mul_f32_e32 v35, v35, v15
	v_mul_f32_e32 v36, v36, v15
	v_mul_f32_e32 v37, v37, v15
	v_mul_f32_e32 v38, v38, v15
	v_mul_f32_e32 v39, v39, v15
	v_mul_f32_e32 v40, v40, v15
	v_mul_f32_e32 v41, v41, v15
	v_mul_f32_e32 v42, v42, v15
	v_mul_f32_e32 v43, v43, v15
	v_mul_f32_e32 v44, v44, v15
	v_mul_f32_e32 v45, v45, v15
	v_mul_f32_e32 v46, v46, v15
	v_mul_f32_e32 v47, v47, v15
	v_mul_f32_e32 v48, v48, v15
	v_mul_f32_e32 v49, v49, v15
	v_sub_f32_e32 v2, v2, v16
	v_sub_f32_e32 v3, v3, v16
	v_sub_f32_e32 v4, v4, v16
	v_sub_f32_e32 v5, v5, v16
	v_sub_f32_e32 v6, v6, v16
	v_sub_f32_e32 v7, v7, v16
	v_sub_f32_e32 v8, v8, v16
	v_sub_f32_e32 v9, v9, v16
	s_branch .Lsel_noupd_Aa

; __device__ __forceinline__ float ex2(float x) { return __builtin_amdgcn_exp2f(x); }
; __device__ __forceinline__ float xq_max(float v) { const auto r = __builtin_amdgcn_permlane16_swap(__float_as_uint(v), __float_as_uint(v), false, false); return xhalf_max(fmaxf(__uint_as_float(r[0]), __uint_as_float(r[1]))); }
; __device__ __forceinline__ void flash16_compute(bool domask, const bf16x8 (&kf)[4], const bf16x8 (&vf)[4], const bf16x8 (&q)[2], int x0, unsigned span, float& m, float& l, f32x4v (&O)[4]) {
;     ...
;     mx = xq_max(mx);
;     const bool upd = mx > m + SM_THR;
;     if (__ballot(upd) != 0ull) {
;         const float mn = upd ? mx : m, alpha = ex2(m - mn); l *= alpha;
; #pragma unroll
;         for (int dt = 0; dt < 4; ++dt) O[dt] = O[dt] * alpha;
;         m = mn;
;     }
.Lsel_upd_Ab:
	v_mov_b32_e32 v16, v14
	s_nop 1
	v_permlane16_swap_b32_e32 v14, v16
	v_max_f32_e32 v14, v14, v16
	v_mov_b32_e32 v16, v14
	s_nop 1
	v_permlane32_swap_b32_e32 v14, v16
	v_max_f32_e32 v14, v14, v16
	v_cmp_gt_f32_e32 vcc, v14, v95
	s_nop 1
	v_cndmask_b32_e32 v16, 0, v14, vcc
	v_sub_f32_e32 v17, v14, v241
	v_cndmask_b32_e32 v17, v237, v17, vcc
	v_sub_f32_e32 v15, v237, v17
	v_exp_f32_e32 v15, v15
	v_mov_b32_e32 v237, v17
	v_cndmask_b32_e64 v241, v241, -v17, vcc
	v_cndmask_b32_e32 v95, v95, v96, vcc
	v_mul_f32_e32 v239, v239, v15
	v_mul_f32_e32 v18, v18, v15
	v_mul_f32_e32 v19, v19, v15
	v_mul_f32_e32 v20, v20, v15
	v_mul_f32_e32 v21, v21, v15
	v_mul_f32_e32 v22, v22, v15
	v_mul_f32_e32 v23, v23, v15
	v_mul_f32_e32 v24, v24, v15
	v_mul_f32_e32 v25, v25, v15
	v_mul_f32_e32 v26, v26, v15
	v_mul_f32_e32 v27, v27, v15
	v_mul_f32_e32 v28, v28, v15
	v_mul_f32_e32 v29, v29, v15
	v_mul_f32_e32 v30, v30, v15
	v_mul_f32_e32 v31, v31, v15
	v_mul_f32_e32 v32, v32, v15
	v_mul_f32_e32 v33, v33, v15
	v_sub_f32_e32 v2, v2, v16
	v_sub_f32_e32 v3, v3, v16
	v_sub_f32_e32 v4, v4, v16
	v_sub_f32_e32 v5, v5, v16
	v_sub_f32_e32 v6, v6, v16
	v_sub_f32_e32 v7, v7, v16
	v_sub_f32_e32 v8, v8, v16
	v_sub_f32_e32 v9, v9, v16
	s_branch .Lsel_noupd_Ab
